# convert_weights: 32 tile loads issued back-to-back per item (was 1-2 in flight); K-seam gate hook loads batched
# speedup vs baseline: 1.0391x; 1.0391x over previous
.LBB0_150:
	s_lshl_b32 s14, s39, 6
	s_cmp_lt_i32 s2, 0
	s_mov_b64 s[26:27], -1
	s_cbranch_scc1 .LBB0_216
	s_lshl_b64 s[26:27], s[2:3], 2
	s_add_u32 s4, s4, s26
	v_add_u32_e32 v8, s14, v5
	s_addc_u32 s5, s5, s27
	v_ashrrev_i32_e32 v9, 31, v8
	v_lshl_add_u64 v[6:7], s[4:5], 0, v[2:3]
	v_mul_lo_u32 v22, s10, v9
	v_mul_lo_u32 v23, s11, v8
	v_mad_u64_u32 v[10:11], s[4:5], s10, v8, 0
	v_add3_u32 v11, v11, v22, v23
	v_lshl_add_u64 v[10:11], v[10:11], 2, v[6:7]
	s_lshl_b64 s[26:27], s[10:11], 3
	global_load_dword v190, v[10:11], off nt
	v_lshl_add_u64 v[10:11], v[10:11], 0, s[26:27]
	global_load_dword v191, v[10:11], off nt
	v_lshl_add_u64 v[10:11], v[10:11], 0, s[26:27]
	global_load_dword v192, v[10:11], off nt
	v_lshl_add_u64 v[10:11], v[10:11], 0, s[26:27]
	global_load_dword v193, v[10:11], off nt
	v_lshl_add_u64 v[10:11], v[10:11], 0, s[26:27]
	global_load_dword v194, v[10:11], off nt
	v_lshl_add_u64 v[10:11], v[10:11], 0, s[26:27]
	global_load_dword v195, v[10:11], off nt
	v_lshl_add_u64 v[10:11], v[10:11], 0, s[26:27]
	global_load_dword v196, v[10:11], off nt
	v_lshl_add_u64 v[10:11], v[10:11], 0, s[26:27]
	global_load_dword v197, v[10:11], off nt
	v_lshl_add_u64 v[10:11], v[10:11], 0, s[26:27]
	global_load_dword v198, v[10:11], off nt
	v_lshl_add_u64 v[10:11], v[10:11], 0, s[26:27]
	global_load_dword v199, v[10:11], off nt
	v_lshl_add_u64 v[10:11], v[10:11], 0, s[26:27]
	global_load_dword v200, v[10:11], off nt
	v_lshl_add_u64 v[10:11], v[10:11], 0, s[26:27]
	global_load_dword v201, v[10:11], off nt
	v_lshl_add_u64 v[10:11], v[10:11], 0, s[26:27]
	global_load_dword v202, v[10:11], off nt
	v_lshl_add_u64 v[10:11], v[10:11], 0, s[26:27]
	global_load_dword v203, v[10:11], off nt
	v_lshl_add_u64 v[10:11], v[10:11], 0, s[26:27]
	global_load_dword v204, v[10:11], off nt
	v_lshl_add_u64 v[10:11], v[10:11], 0, s[26:27]
	global_load_dword v205, v[10:11], off nt
	v_lshl_add_u64 v[10:11], v[10:11], 0, s[26:27]
	global_load_dword v206, v[10:11], off nt
	v_lshl_add_u64 v[10:11], v[10:11], 0, s[26:27]
	global_load_dword v207, v[10:11], off nt
	v_lshl_add_u64 v[10:11], v[10:11], 0, s[26:27]
	global_load_dword v208, v[10:11], off nt
	v_lshl_add_u64 v[10:11], v[10:11], 0, s[26:27]
	global_load_dword v209, v[10:11], off nt
	v_lshl_add_u64 v[10:11], v[10:11], 0, s[26:27]
	global_load_dword v210, v[10:11], off nt
	v_lshl_add_u64 v[10:11], v[10:11], 0, s[26:27]
	global_load_dword v211, v[10:11], off nt
	v_lshl_add_u64 v[10:11], v[10:11], 0, s[26:27]
	global_load_dword v212, v[10:11], off nt
	v_lshl_add_u64 v[10:11], v[10:11], 0, s[26:27]
	global_load_dword v213, v[10:11], off nt
	v_lshl_add_u64 v[10:11], v[10:11], 0, s[26:27]
	global_load_dword v214, v[10:11], off nt
	v_lshl_add_u64 v[10:11], v[10:11], 0, s[26:27]
	global_load_dword v215, v[10:11], off nt
	v_lshl_add_u64 v[10:11], v[10:11], 0, s[26:27]
	global_load_dword v216, v[10:11], off nt
	v_lshl_add_u64 v[10:11], v[10:11], 0, s[26:27]
	global_load_dword v217, v[10:11], off nt
	v_lshl_add_u64 v[10:11], v[10:11], 0, s[26:27]
	global_load_dword v218, v[10:11], off nt
	v_lshl_add_u64 v[10:11], v[10:11], 0, s[26:27]
	global_load_dword v219, v[10:11], off nt
	v_lshl_add_u64 v[10:11], v[10:11], 0, s[26:27]
	global_load_dword v220, v[10:11], off nt
	v_lshl_add_u64 v[10:11], v[10:11], 0, s[26:27]
	global_load_dword v221, v[10:11], off nt
	s_cmp_lg_u64 s[20:21], 0
	s_cbranch_scc0 .Ltr0_noscale
	v_lshl_add_u64 v[6:7], v[8:9], 2, s[20:21]
	global_load_dword v222, v[6:7], off
	global_load_dword v223, v[6:7], off offset:8
	global_load_dword v224, v[6:7], off offset:16
	global_load_dword v225, v[6:7], off offset:24
	global_load_dword v226, v[6:7], off offset:32
	global_load_dword v227, v[6:7], off offset:40
	global_load_dword v228, v[6:7], off offset:48
	global_load_dword v229, v[6:7], off offset:56
	global_load_dword v230, v[6:7], off offset:64
	global_load_dword v231, v[6:7], off offset:72
	global_load_dword v232, v[6:7], off offset:80
	global_load_dword v233, v[6:7], off offset:88
	global_load_dword v234, v[6:7], off offset:96
	global_load_dword v235, v[6:7], off offset:104
	global_load_dword v236, v[6:7], off offset:112
	global_load_dword v237, v[6:7], off offset:120
	global_load_dword v238, v[6:7], off offset:128
	global_load_dword v239, v[6:7], off offset:136
	global_load_dword v240, v[6:7], off offset:144
	global_load_dword v241, v[6:7], off offset:152
	global_load_dword v242, v[6:7], off offset:160
	global_load_dword v243, v[6:7], off offset:168
	global_load_dword v244, v[6:7], off offset:176
	global_load_dword v245, v[6:7], off offset:184
	global_load_dword v246, v[6:7], off offset:192
	global_load_dword v247, v[6:7], off offset:200
	global_load_dword v248, v[6:7], off offset:208
	global_load_dword v249, v[6:7], off offset:216
	global_load_dword v250, v[6:7], off offset:224
	global_load_dword v251, v[6:7], off offset:232
	global_load_dword v252, v[6:7], off offset:240
	global_load_dword v253, v[6:7], off offset:248
	s_waitcnt vmcnt(0)
	v_mul_f32_e32 v190, v190, v222
	v_mul_f32_e32 v191, v191, v223
	v_mul_f32_e32 v192, v192, v224
	v_mul_f32_e32 v193, v193, v225
	v_mul_f32_e32 v194, v194, v226
	v_mul_f32_e32 v195, v195, v227
	v_mul_f32_e32 v196, v196, v228
	v_mul_f32_e32 v197, v197, v229
	v_mul_f32_e32 v198, v198, v230
	v_mul_f32_e32 v199, v199, v231
	v_mul_f32_e32 v200, v200, v232
	v_mul_f32_e32 v201, v201, v233
	v_mul_f32_e32 v202, v202, v234
	v_mul_f32_e32 v203, v203, v235
	v_mul_f32_e32 v204, v204, v236
	v_mul_f32_e32 v205, v205, v237
	v_mul_f32_e32 v206, v206, v238
	v_mul_f32_e32 v207, v207, v239
	v_mul_f32_e32 v208, v208, v240
	v_mul_f32_e32 v209, v209, v241
	v_mul_f32_e32 v210, v210, v242
	v_mul_f32_e32 v211, v211, v243
	v_mul_f32_e32 v212, v212, v244
	v_mul_f32_e32 v213, v213, v245
	v_mul_f32_e32 v214, v214, v246
	v_mul_f32_e32 v215, v215, v247
	v_mul_f32_e32 v216, v216, v248
	v_mul_f32_e32 v217, v217, v249
	v_mul_f32_e32 v218, v218, v250
	v_mul_f32_e32 v219, v219, v251
	v_mul_f32_e32 v220, v220, v252
	v_mul_f32_e32 v221, v221, v253
.Ltr0_noscale:
	s_waitcnt vmcnt(0)
	ds_write_b32 v21, v190
	ds_write_b32 v21, v191 offset:264
	ds_write_b32 v21, v192 offset:528
	ds_write_b32 v21, v193 offset:792
	ds_write_b32 v21, v194 offset:1056
	ds_write_b32 v21, v195 offset:1320
	ds_write_b32 v21, v196 offset:1584
	ds_write_b32 v21, v197 offset:1848
	ds_write_b32 v21, v198 offset:2112
	ds_write_b32 v21, v199 offset:2376
	ds_write_b32 v21, v200 offset:2640
	ds_write_b32 v21, v201 offset:2904
	ds_write_b32 v21, v202 offset:3168
	ds_write_b32 v21, v203 offset:3432
	ds_write_b32 v21, v204 offset:3696
	ds_write_b32 v21, v205 offset:3960
	ds_write_b32 v21, v206 offset:4224
	ds_write_b32 v21, v207 offset:4488
	ds_write_b32 v21, v208 offset:4752
	ds_write_b32 v21, v209 offset:5016
	ds_write_b32 v21, v210 offset:5280
	ds_write_b32 v21, v211 offset:5544
	ds_write_b32 v21, v212 offset:5808
	ds_write_b32 v21, v213 offset:6072
	ds_write_b32 v21, v214 offset:6336
	ds_write_b32 v21, v215 offset:6600
	ds_write_b32 v21, v216 offset:6864
	ds_write_b32 v21, v217 offset:7128
	ds_write_b32 v21, v218 offset:7392
	ds_write_b32 v21, v219 offset:7656
	ds_write_b32 v21, v220 offset:7920
	ds_write_b32 v21, v221 offset:8184
	v_cndmask_b32_e64 v8, v12, v14, s[12:13]
	s_waitcnt lgkmcnt(0)
	s_ashr_i32 s15, s14, 31
	v_lshl_add_u32 v24, v8, 2, v13
	s_lshl_b64 s[4:5], s[14:15], 1
	ds_read2_b32 v[8:9], v24 offset1:33
	ds_read2_b32 v[10:11], v24 offset0:66 offset1:99
	ds_read2_b32 v[22:23], v24 offset0:132 offset1:165
	ds_read2_b32 v[24:25], v24 offset0:198 offset1:231
	s_add_u32 s4, s6, s4
	s_addc_u32 s5, s7, s5
	v_lshlrev_b32_e32 v6, 1, v4
	v_mov_b32_e32 v7, v3
	v_lshl_add_u64 v[26:27], s[4:5], 0, v[6:7]
	s_waitcnt lgkmcnt(2)
	v_cvt_pk_bf16_f32 v7, v10, v11
	v_add_u32_e32 v10, s38, v12
	v_ashrrev_i32_e32 v11, 31, v10
	v_cvt_pk_bf16_f32 v6, v8, v9
	s_waitcnt lgkmcnt(1)
	v_cvt_pk_bf16_f32 v8, v22, v23
	v_mul_lo_u32 v22, s8, v11
	v_mul_lo_u32 v23, s9, v10
	v_mad_u64_u32 v[10:11], s[4:5], s8, v10, 0
	v_add3_u32 v11, v11, v22, v23
	v_cndmask_b32_e64 v22, v15, v16, s[12:13]
	v_lshl_add_u32 v30, v22, 2, v13
	s_waitcnt lgkmcnt(0)
	v_cvt_pk_bf16_f32 v9, v24, v25
	v_lshl_add_u64 v[10:11], v[10:11], 1, v[26:27]
	ds_read2_b32 v[22:23], v30 offset1:33
	ds_read2_b32 v[24:25], v30 offset0:66 offset1:99
	ds_read2_b32 v[28:29], v30 offset0:132 offset1:165
	ds_read2_b32 v[30:31], v30 offset0:198 offset1:231
	global_store_dwordx4 v[10:11], v[6:9], off
	v_add_u32_e32 v10, s38, v15
	v_ashrrev_i32_e32 v11, 31, v10
	s_waitcnt lgkmcnt(3)
	v_cvt_pk_bf16_f32 v6, v22, v23
	v_mul_lo_u32 v22, s8, v11
	v_mul_lo_u32 v23, s9, v10
	v_mad_u64_u32 v[10:11], s[4:5], s8, v10, 0
	v_add3_u32 v11, v11, v22, v23
	v_cndmask_b32_e64 v22, v17, v18, s[12:13]
	s_waitcnt lgkmcnt(0)
	v_cvt_pk_bf16_f32 v9, v30, v31
	v_lshl_add_u32 v30, v22, 2, v13
	v_cvt_pk_bf16_f32 v7, v24, v25
	v_cvt_pk_bf16_f32 v8, v28, v29
	v_lshl_add_u64 v[10:11], v[10:11], 1, v[26:27]
	ds_read2_b32 v[22:23], v30 offset1:33
	ds_read2_b32 v[24:25], v30 offset0:66 offset1:99
	ds_read2_b32 v[28:29], v30 offset0:132 offset1:165
	ds_read2_b32 v[30:31], v30 offset0:198 offset1:231
	global_store_dwordx4 v[10:11], v[6:9], off
	v_add_u32_e32 v10, s38, v17
	v_ashrrev_i32_e32 v11, 31, v10
	s_waitcnt lgkmcnt(3)
	v_cvt_pk_bf16_f32 v6, v22, v23
	v_mul_lo_u32 v22, s8, v11
	v_mul_lo_u32 v23, s9, v10
	v_mad_u64_u32 v[10:11], s[4:5], s8, v10, 0
	v_add3_u32 v11, v11, v22, v23
	v_cndmask_b32_e64 v22, v19, v20, s[12:13]
	s_waitcnt lgkmcnt(0)
	v_cvt_pk_bf16_f32 v9, v30, v31
	v_lshl_add_u32 v30, v22, 2, v13
	v_cvt_pk_bf16_f32 v7, v24, v25
	v_cvt_pk_bf16_f32 v8, v28, v29
	v_lshl_add_u64 v[10:11], v[10:11], 1, v[26:27]
	ds_read2_b32 v[22:23], v30 offset1:33
	ds_read2_b32 v[24:25], v30 offset0:66 offset1:99
	ds_read2_b32 v[28:29], v30 offset0:132 offset1:165
	ds_read2_b32 v[30:31], v30 offset0:198 offset1:231
	global_store_dwordx4 v[10:11], v[6:9], off
	v_add_u32_e32 v10, s38, v19
	v_ashrrev_i32_e32 v11, 31, v10
	s_waitcnt lgkmcnt(3)
	v_cvt_pk_bf16_f32 v6, v22, v23
	v_mul_lo_u32 v22, s8, v11
	v_mul_lo_u32 v23, s9, v10
	v_mad_u64_u32 v[10:11], s[4:5], s8, v10, 0
	v_add3_u32 v11, v11, v22, v23
	s_waitcnt lgkmcnt(2)
	v_cvt_pk_bf16_f32 v7, v24, v25
	s_waitcnt lgkmcnt(1)
	v_cvt_pk_bf16_f32 v8, v28, v29
	s_waitcnt lgkmcnt(0)
	v_cvt_pk_bf16_f32 v9, v30, v31
	v_lshl_add_u64 v[10:11], v[10:11], 1, v[26:27]
	global_store_dwordx4 v[10:11], v[6:9], off
	s_waitcnt lgkmcnt(0)
	s_branch .LBB0_73

.LBB0_1298:
	v_mov_b32_e32 v144, v148
	v_mov_b32_e32 v145, v149
	s_cmpk_eq_i32 s46, 0x600
	v_add_u32_e32 v152, s82, v144
	v_lshlrev_b32_e32 v146, 3, v145
	s_cselect_b32 s66, 0, 0x1000
	s_lshl_b64 s[26:27], s[44:45], 1
	s_mov_b32 s15, s67
	v_mul_u32_u24_e32 v153, 0x3000, v152
	v_lshl_add_u32 v153, v146, 1, v153
	s_add_i32 s2, s66, s26
	s_add_i32 s2, s2, s14
	v_add_u32_e32 v153, s2, v153
	s_add_u32 s100, s10, 0x1000
	s_addc_u32 s101, s11, 0
	global_load_dwordx4 v[168:171], v153, s[10:11]
	global_load_dwordx4 v[172:175], v153, s[100:101]
	global_load_dwordx4 v[176:179], v153, s[10:11] offset:256
	global_load_dwordx4 v[180:183], v153, s[100:101] offset:256
	v_add_u32_e32 v155, 0x30000, v153
	global_load_dwordx4 v[184:187], v155, s[10:11]
	global_load_dwordx4 v[188:191], v155, s[100:101]
	global_load_dwordx4 v[192:195], v155, s[10:11] offset:256
	global_load_dwordx4 v[196:199], v155, s[100:101] offset:256
	s_waitcnt vmcnt(0)
	v_and_b32_e32 v157, 0xffff0000, v172
	v_lshlrev_b32_e32 v156, 16, v172
	v_rcp_f32_e32 v157, v157
	v_rcp_f32_e32 v156, v156
	v_lshlrev_b32_e32 v158, 16, v168
	v_and_b32_e32 v159, 0xffff0000, v168
	v_pk_mul_f32 v[156:157], v[156:157], v[158:159]
	v_and_b32_e32 v161, 0xffff0000, v173
	v_lshlrev_b32_e32 v160, 16, v173
	v_rcp_f32_e32 v161, v161
	v_rcp_f32_e32 v160, v160
	v_lshlrev_b32_e32 v162, 16, v169
	v_and_b32_e32 v163, 0xffff0000, v169
	v_pk_mul_f32 v[126:127], v[126:127], v[156:157]
	v_pk_mul_f32 v[160:161], v[160:161], v[162:163]
	v_and_b32_e32 v157, 0xffff0000, v174
	v_lshlrev_b32_e32 v156, 16, v174
	v_rcp_f32_e32 v157, v157
	v_rcp_f32_e32 v156, v156
	v_lshlrev_b32_e32 v158, 16, v170
	v_and_b32_e32 v159, 0xffff0000, v170
	v_pk_mul_f32 v[128:129], v[128:129], v[160:161]
	v_pk_mul_f32 v[156:157], v[156:157], v[158:159]
	v_and_b32_e32 v161, 0xffff0000, v175
	v_lshlrev_b32_e32 v160, 16, v175
	v_rcp_f32_e32 v161, v161
	v_rcp_f32_e32 v160, v160
	v_lshlrev_b32_e32 v162, 16, v171
	v_and_b32_e32 v163, 0xffff0000, v171
	v_pk_mul_f32 v[122:123], v[122:123], v[156:157]
	v_pk_mul_f32 v[160:161], v[160:161], v[162:163]
	v_and_b32_e32 v157, 0xffff0000, v180
	v_lshlrev_b32_e32 v156, 16, v180
	v_rcp_f32_e32 v157, v157
	v_rcp_f32_e32 v156, v156
	v_lshlrev_b32_e32 v158, 16, v176
	v_and_b32_e32 v159, 0xffff0000, v176
	v_pk_mul_f32 v[124:125], v[124:125], v[160:161]
	v_pk_mul_f32 v[156:157], v[156:157], v[158:159]
	v_and_b32_e32 v161, 0xffff0000, v181
	v_lshlrev_b32_e32 v160, 16, v181
	v_rcp_f32_e32 v161, v161
	v_rcp_f32_e32 v160, v160
	v_lshlrev_b32_e32 v162, 16, v177
	v_and_b32_e32 v163, 0xffff0000, v177
	v_pk_mul_f32 v[118:119], v[118:119], v[156:157]
	v_pk_mul_f32 v[160:161], v[160:161], v[162:163]
	v_and_b32_e32 v157, 0xffff0000, v182
	v_lshlrev_b32_e32 v156, 16, v182
	v_rcp_f32_e32 v157, v157
	v_rcp_f32_e32 v156, v156
	v_lshlrev_b32_e32 v158, 16, v178
	v_and_b32_e32 v159, 0xffff0000, v178
	v_pk_mul_f32 v[120:121], v[120:121], v[160:161]
	v_pk_mul_f32 v[156:157], v[156:157], v[158:159]
	v_and_b32_e32 v161, 0xffff0000, v183
	v_lshlrev_b32_e32 v160, 16, v183
	v_rcp_f32_e32 v161, v161
	v_rcp_f32_e32 v160, v160
	v_lshlrev_b32_e32 v162, 16, v179
	v_and_b32_e32 v163, 0xffff0000, v179
	v_pk_mul_f32 v[114:115], v[114:115], v[156:157]
	v_pk_mul_f32 v[160:161], v[160:161], v[162:163]
	v_and_b32_e32 v157, 0xffff0000, v188
	v_lshlrev_b32_e32 v156, 16, v188
	v_rcp_f32_e32 v157, v157
	v_rcp_f32_e32 v156, v156
	v_lshlrev_b32_e32 v158, 16, v184
	v_and_b32_e32 v159, 0xffff0000, v184
	v_pk_mul_f32 v[116:117], v[116:117], v[160:161]
	v_pk_mul_f32 v[156:157], v[156:157], v[158:159]
	v_and_b32_e32 v161, 0xffff0000, v189
	v_lshlrev_b32_e32 v160, 16, v189
	v_rcp_f32_e32 v161, v161
	v_rcp_f32_e32 v160, v160
	v_lshlrev_b32_e32 v162, 16, v185
	v_and_b32_e32 v163, 0xffff0000, v185
	v_pk_mul_f32 v[110:111], v[110:111], v[156:157]
	v_pk_mul_f32 v[160:161], v[160:161], v[162:163]
	v_and_b32_e32 v157, 0xffff0000, v190
	v_lshlrev_b32_e32 v156, 16, v190
	v_rcp_f32_e32 v157, v157
	v_rcp_f32_e32 v156, v156
	v_lshlrev_b32_e32 v158, 16, v186
	v_and_b32_e32 v159, 0xffff0000, v186
	v_pk_mul_f32 v[112:113], v[112:113], v[160:161]
	v_pk_mul_f32 v[156:157], v[156:157], v[158:159]
	v_and_b32_e32 v161, 0xffff0000, v191
	v_lshlrev_b32_e32 v160, 16, v191
	v_rcp_f32_e32 v161, v161
	v_rcp_f32_e32 v160, v160
	v_lshlrev_b32_e32 v162, 16, v187
	v_and_b32_e32 v163, 0xffff0000, v187
	v_pk_mul_f32 v[106:107], v[106:107], v[156:157]
	v_pk_mul_f32 v[160:161], v[160:161], v[162:163]
	v_and_b32_e32 v157, 0xffff0000, v196
	v_lshlrev_b32_e32 v156, 16, v196
	v_rcp_f32_e32 v157, v157
	v_rcp_f32_e32 v156, v156
	v_lshlrev_b32_e32 v158, 16, v192
	v_and_b32_e32 v159, 0xffff0000, v192
	v_pk_mul_f32 v[108:109], v[108:109], v[160:161]
	v_pk_mul_f32 v[156:157], v[156:157], v[158:159]
	v_and_b32_e32 v161, 0xffff0000, v197
	v_lshlrev_b32_e32 v160, 16, v197
	v_rcp_f32_e32 v161, v161
	v_rcp_f32_e32 v160, v160
	v_lshlrev_b32_e32 v162, 16, v193
	v_and_b32_e32 v163, 0xffff0000, v193
	v_pk_mul_f32 v[102:103], v[102:103], v[156:157]
	v_pk_mul_f32 v[160:161], v[160:161], v[162:163]
	v_and_b32_e32 v157, 0xffff0000, v198
	v_lshlrev_b32_e32 v156, 16, v198
	v_rcp_f32_e32 v157, v157
	v_rcp_f32_e32 v156, v156
	v_lshlrev_b32_e32 v158, 16, v194
	v_and_b32_e32 v159, 0xffff0000, v194
	v_pk_mul_f32 v[104:105], v[104:105], v[160:161]
	v_pk_mul_f32 v[156:157], v[156:157], v[158:159]
	v_and_b32_e32 v161, 0xffff0000, v199
	v_lshlrev_b32_e32 v160, 16, v199
	v_rcp_f32_e32 v161, v161
	v_rcp_f32_e32 v160, v160
	v_lshlrev_b32_e32 v162, 16, v195
	v_and_b32_e32 v163, 0xffff0000, v195
	v_pk_mul_f32 v[98:99], v[98:99], v[156:157]
	v_pk_mul_f32 v[160:161], v[160:161], v[162:163]
	s_nop 0
	v_pk_mul_f32 v[100:101], v[100:101], v[160:161]
	v_add_u32_e32 v154, 0x60000, v153
	global_load_dwordx4 v[168:171], v154, s[10:11]
	global_load_dwordx4 v[172:175], v154, s[100:101]
	global_load_dwordx4 v[176:179], v154, s[10:11] offset:256
	global_load_dwordx4 v[180:183], v154, s[100:101] offset:256
	v_add_u32_e32 v155, 0x90000, v153
	global_load_dwordx4 v[184:187], v155, s[10:11]
	global_load_dwordx4 v[188:191], v155, s[100:101]
	global_load_dwordx4 v[192:195], v155, s[10:11] offset:256
	global_load_dwordx4 v[196:199], v155, s[100:101] offset:256
	s_waitcnt vmcnt(0)
	v_and_b32_e32 v157, 0xffff0000, v172
	v_lshlrev_b32_e32 v156, 16, v172
	v_rcp_f32_e32 v157, v157
	v_rcp_f32_e32 v156, v156
	v_lshlrev_b32_e32 v158, 16, v168
	v_and_b32_e32 v159, 0xffff0000, v168
	v_pk_mul_f32 v[156:157], v[156:157], v[158:159]
	v_and_b32_e32 v161, 0xffff0000, v173
	v_lshlrev_b32_e32 v160, 16, v173
	v_rcp_f32_e32 v161, v161
	v_rcp_f32_e32 v160, v160
	v_lshlrev_b32_e32 v162, 16, v169
	v_and_b32_e32 v163, 0xffff0000, v169
	v_pk_mul_f32 v[94:95], v[94:95], v[156:157]
	v_pk_mul_f32 v[160:161], v[160:161], v[162:163]
	v_and_b32_e32 v157, 0xffff0000, v174
	v_lshlrev_b32_e32 v156, 16, v174
	v_rcp_f32_e32 v157, v157
	v_rcp_f32_e32 v156, v156
	v_lshlrev_b32_e32 v158, 16, v170
	v_and_b32_e32 v159, 0xffff0000, v170
	v_pk_mul_f32 v[96:97], v[96:97], v[160:161]
	v_pk_mul_f32 v[156:157], v[156:157], v[158:159]
	v_and_b32_e32 v161, 0xffff0000, v175
	v_lshlrev_b32_e32 v160, 16, v175
	v_rcp_f32_e32 v161, v161
	v_rcp_f32_e32 v160, v160
	v_lshlrev_b32_e32 v162, 16, v171
	v_and_b32_e32 v163, 0xffff0000, v171
	v_pk_mul_f32 v[90:91], v[90:91], v[156:157]
	v_pk_mul_f32 v[160:161], v[160:161], v[162:163]
	v_and_b32_e32 v157, 0xffff0000, v180
	v_lshlrev_b32_e32 v156, 16, v180
	v_rcp_f32_e32 v157, v157
	v_rcp_f32_e32 v156, v156
	v_lshlrev_b32_e32 v158, 16, v176
	v_and_b32_e32 v159, 0xffff0000, v176
	v_pk_mul_f32 v[92:93], v[92:93], v[160:161]
	v_pk_mul_f32 v[156:157], v[156:157], v[158:159]
	v_and_b32_e32 v161, 0xffff0000, v181
	v_lshlrev_b32_e32 v160, 16, v181
	v_rcp_f32_e32 v161, v161
	v_rcp_f32_e32 v160, v160
	v_lshlrev_b32_e32 v162, 16, v177
	v_and_b32_e32 v163, 0xffff0000, v177
	v_pk_mul_f32 v[86:87], v[86:87], v[156:157]
	v_pk_mul_f32 v[160:161], v[160:161], v[162:163]
	v_and_b32_e32 v157, 0xffff0000, v182
	v_lshlrev_b32_e32 v156, 16, v182
	v_rcp_f32_e32 v157, v157
	v_rcp_f32_e32 v156, v156
	v_lshlrev_b32_e32 v158, 16, v178
	v_and_b32_e32 v159, 0xffff0000, v178
	v_pk_mul_f32 v[88:89], v[88:89], v[160:161]
	v_pk_mul_f32 v[156:157], v[156:157], v[158:159]
	v_and_b32_e32 v161, 0xffff0000, v183
	v_lshlrev_b32_e32 v160, 16, v183
	v_rcp_f32_e32 v161, v161
	v_rcp_f32_e32 v160, v160
	v_lshlrev_b32_e32 v162, 16, v179
	v_and_b32_e32 v163, 0xffff0000, v179
	v_pk_mul_f32 v[82:83], v[82:83], v[156:157]
	v_pk_mul_f32 v[160:161], v[160:161], v[162:163]
	v_and_b32_e32 v157, 0xffff0000, v188
	v_lshlrev_b32_e32 v156, 16, v188
	v_rcp_f32_e32 v157, v157
	v_rcp_f32_e32 v156, v156
	v_lshlrev_b32_e32 v158, 16, v184
	v_and_b32_e32 v159, 0xffff0000, v184
	v_pk_mul_f32 v[84:85], v[84:85], v[160:161]
	v_pk_mul_f32 v[156:157], v[156:157], v[158:159]
	v_and_b32_e32 v161, 0xffff0000, v189
	v_lshlrev_b32_e32 v160, 16, v189
	v_rcp_f32_e32 v161, v161
	v_rcp_f32_e32 v160, v160
	v_lshlrev_b32_e32 v162, 16, v185
	v_and_b32_e32 v163, 0xffff0000, v185
	v_pk_mul_f32 v[78:79], v[78:79], v[156:157]
	v_pk_mul_f32 v[160:161], v[160:161], v[162:163]
	v_and_b32_e32 v157, 0xffff0000, v190
	v_lshlrev_b32_e32 v156, 16, v190
	v_rcp_f32_e32 v157, v157
	v_rcp_f32_e32 v156, v156
	v_lshlrev_b32_e32 v158, 16, v186
	v_and_b32_e32 v159, 0xffff0000, v186
	v_pk_mul_f32 v[80:81], v[80:81], v[160:161]
	v_pk_mul_f32 v[156:157], v[156:157], v[158:159]
	v_and_b32_e32 v161, 0xffff0000, v191
	v_lshlrev_b32_e32 v160, 16, v191
	v_rcp_f32_e32 v161, v161
	v_rcp_f32_e32 v160, v160
	v_lshlrev_b32_e32 v162, 16, v187
	v_and_b32_e32 v163, 0xffff0000, v187
	v_pk_mul_f32 v[74:75], v[74:75], v[156:157]
	v_pk_mul_f32 v[160:161], v[160:161], v[162:163]
	v_and_b32_e32 v157, 0xffff0000, v196
	v_lshlrev_b32_e32 v156, 16, v196
	v_rcp_f32_e32 v157, v157
	v_rcp_f32_e32 v156, v156
	v_lshlrev_b32_e32 v158, 16, v192
	v_and_b32_e32 v159, 0xffff0000, v192
	v_pk_mul_f32 v[76:77], v[76:77], v[160:161]
	v_pk_mul_f32 v[156:157], v[156:157], v[158:159]
	v_and_b32_e32 v161, 0xffff0000, v197
	v_lshlrev_b32_e32 v160, 16, v197
	v_rcp_f32_e32 v161, v161
	v_rcp_f32_e32 v160, v160
	v_lshlrev_b32_e32 v162, 16, v193
	v_and_b32_e32 v163, 0xffff0000, v193
	v_pk_mul_f32 v[70:71], v[70:71], v[156:157]
	v_pk_mul_f32 v[160:161], v[160:161], v[162:163]
	v_and_b32_e32 v157, 0xffff0000, v198
	v_lshlrev_b32_e32 v156, 16, v198
	v_rcp_f32_e32 v157, v157
	v_rcp_f32_e32 v156, v156
	v_lshlrev_b32_e32 v158, 16, v194
	v_and_b32_e32 v159, 0xffff0000, v194
	v_pk_mul_f32 v[72:73], v[72:73], v[160:161]
	v_pk_mul_f32 v[156:157], v[156:157], v[158:159]
	v_and_b32_e32 v161, 0xffff0000, v199
	v_lshlrev_b32_e32 v160, 16, v199
	v_rcp_f32_e32 v161, v161
	v_rcp_f32_e32 v160, v160
	v_lshlrev_b32_e32 v162, 16, v195
	v_and_b32_e32 v163, 0xffff0000, v195
	v_pk_mul_f32 v[66:67], v[66:67], v[156:157]
	v_pk_mul_f32 v[160:161], v[160:161], v[162:163]
	s_nop 0
	v_pk_mul_f32 v[68:69], v[68:69], v[160:161]
	v_add_u32_e32 v154, 0x180000, v153
	global_load_dwordx4 v[168:171], v154, s[10:11]
	global_load_dwordx4 v[172:175], v154, s[100:101]
	global_load_dwordx4 v[176:179], v154, s[10:11] offset:256
	global_load_dwordx4 v[180:183], v154, s[100:101] offset:256
	v_add_u32_e32 v155, 0x1b0000, v153
	global_load_dwordx4 v[184:187], v155, s[10:11]
	global_load_dwordx4 v[188:191], v155, s[100:101]
	global_load_dwordx4 v[192:195], v155, s[10:11] offset:256
	global_load_dwordx4 v[196:199], v155, s[100:101] offset:256
	s_waitcnt vmcnt(0)
	v_and_b32_e32 v157, 0xffff0000, v172
	v_lshlrev_b32_e32 v156, 16, v172
	v_rcp_f32_e32 v157, v157
	v_rcp_f32_e32 v156, v156
	v_lshlrev_b32_e32 v158, 16, v168
	v_and_b32_e32 v159, 0xffff0000, v168
	v_pk_mul_f32 v[156:157], v[156:157], v[158:159]
	v_and_b32_e32 v161, 0xffff0000, v173
	v_lshlrev_b32_e32 v160, 16, v173
	v_rcp_f32_e32 v161, v161
	v_rcp_f32_e32 v160, v160
	v_lshlrev_b32_e32 v162, 16, v169
	v_and_b32_e32 v163, 0xffff0000, v169
	v_pk_mul_f32 v[62:63], v[62:63], v[156:157]
	v_pk_mul_f32 v[160:161], v[160:161], v[162:163]
	v_and_b32_e32 v157, 0xffff0000, v174
	v_lshlrev_b32_e32 v156, 16, v174
	v_rcp_f32_e32 v157, v157
	v_rcp_f32_e32 v156, v156
	v_lshlrev_b32_e32 v158, 16, v170
	v_and_b32_e32 v159, 0xffff0000, v170
	v_pk_mul_f32 v[64:65], v[64:65], v[160:161]
	v_pk_mul_f32 v[156:157], v[156:157], v[158:159]
	v_and_b32_e32 v161, 0xffff0000, v175
	v_lshlrev_b32_e32 v160, 16, v175
	v_rcp_f32_e32 v161, v161
	v_rcp_f32_e32 v160, v160
	v_lshlrev_b32_e32 v162, 16, v171
	v_and_b32_e32 v163, 0xffff0000, v171
	v_pk_mul_f32 v[58:59], v[58:59], v[156:157]
	v_pk_mul_f32 v[160:161], v[160:161], v[162:163]
	v_and_b32_e32 v157, 0xffff0000, v180
	v_lshlrev_b32_e32 v156, 16, v180
	v_rcp_f32_e32 v157, v157
	v_rcp_f32_e32 v156, v156
	v_lshlrev_b32_e32 v158, 16, v176
	v_and_b32_e32 v159, 0xffff0000, v176
	v_pk_mul_f32 v[60:61], v[60:61], v[160:161]
	v_pk_mul_f32 v[156:157], v[156:157], v[158:159]
	v_and_b32_e32 v161, 0xffff0000, v181
	v_lshlrev_b32_e32 v160, 16, v181
	v_rcp_f32_e32 v161, v161
	v_rcp_f32_e32 v160, v160
	v_lshlrev_b32_e32 v162, 16, v177
	v_and_b32_e32 v163, 0xffff0000, v177
	v_pk_mul_f32 v[54:55], v[54:55], v[156:157]
	v_pk_mul_f32 v[160:161], v[160:161], v[162:163]
	v_and_b32_e32 v157, 0xffff0000, v182
	v_lshlrev_b32_e32 v156, 16, v182
	v_rcp_f32_e32 v157, v157
	v_rcp_f32_e32 v156, v156
	v_lshlrev_b32_e32 v158, 16, v178
	v_and_b32_e32 v159, 0xffff0000, v178
	v_pk_mul_f32 v[56:57], v[56:57], v[160:161]
	v_pk_mul_f32 v[156:157], v[156:157], v[158:159]
	v_and_b32_e32 v161, 0xffff0000, v183
	v_lshlrev_b32_e32 v160, 16, v183
	v_rcp_f32_e32 v161, v161
	v_rcp_f32_e32 v160, v160
	v_lshlrev_b32_e32 v162, 16, v179
	v_and_b32_e32 v163, 0xffff0000, v179
	v_pk_mul_f32 v[50:51], v[50:51], v[156:157]
	v_pk_mul_f32 v[160:161], v[160:161], v[162:163]
	v_and_b32_e32 v157, 0xffff0000, v188
	v_lshlrev_b32_e32 v156, 16, v188
	v_rcp_f32_e32 v157, v157
	v_rcp_f32_e32 v156, v156
	v_lshlrev_b32_e32 v158, 16, v184
	v_and_b32_e32 v159, 0xffff0000, v184
	v_pk_mul_f32 v[52:53], v[52:53], v[160:161]
	v_pk_mul_f32 v[156:157], v[156:157], v[158:159]
	v_and_b32_e32 v161, 0xffff0000, v189
	v_lshlrev_b32_e32 v160, 16, v189
	v_rcp_f32_e32 v161, v161
	v_rcp_f32_e32 v160, v160
	v_lshlrev_b32_e32 v162, 16, v185
	v_and_b32_e32 v163, 0xffff0000, v185
	v_pk_mul_f32 v[46:47], v[46:47], v[156:157]
	v_pk_mul_f32 v[160:161], v[160:161], v[162:163]
	v_and_b32_e32 v157, 0xffff0000, v190
	v_lshlrev_b32_e32 v156, 16, v190
	v_rcp_f32_e32 v157, v157
	v_rcp_f32_e32 v156, v156
	v_lshlrev_b32_e32 v158, 16, v186
	v_and_b32_e32 v159, 0xffff0000, v186
	v_pk_mul_f32 v[48:49], v[48:49], v[160:161]
	v_pk_mul_f32 v[156:157], v[156:157], v[158:159]
	v_and_b32_e32 v161, 0xffff0000, v191
	v_lshlrev_b32_e32 v160, 16, v191
	v_rcp_f32_e32 v161, v161
	v_rcp_f32_e32 v160, v160
	v_lshlrev_b32_e32 v162, 16, v187
	v_and_b32_e32 v163, 0xffff0000, v187
	v_pk_mul_f32 v[42:43], v[42:43], v[156:157]
	v_pk_mul_f32 v[160:161], v[160:161], v[162:163]
	v_and_b32_e32 v157, 0xffff0000, v196
	v_lshlrev_b32_e32 v156, 16, v196
	v_rcp_f32_e32 v157, v157
	v_rcp_f32_e32 v156, v156
	v_lshlrev_b32_e32 v158, 16, v192
	v_and_b32_e32 v159, 0xffff0000, v192
	v_pk_mul_f32 v[44:45], v[44:45], v[160:161]
	v_pk_mul_f32 v[156:157], v[156:157], v[158:159]
	v_and_b32_e32 v161, 0xffff0000, v197
	v_lshlrev_b32_e32 v160, 16, v197
	v_rcp_f32_e32 v161, v161
	v_rcp_f32_e32 v160, v160
	v_lshlrev_b32_e32 v162, 16, v193
	v_and_b32_e32 v163, 0xffff0000, v193
	v_pk_mul_f32 v[38:39], v[38:39], v[156:157]
	v_pk_mul_f32 v[160:161], v[160:161], v[162:163]
	v_and_b32_e32 v157, 0xffff0000, v198
	v_lshlrev_b32_e32 v156, 16, v198
	v_rcp_f32_e32 v157, v157
	v_rcp_f32_e32 v156, v156
	v_lshlrev_b32_e32 v158, 16, v194
	v_and_b32_e32 v159, 0xffff0000, v194
	v_pk_mul_f32 v[40:41], v[40:41], v[160:161]
	v_pk_mul_f32 v[156:157], v[156:157], v[158:159]
	v_and_b32_e32 v161, 0xffff0000, v199
	v_lshlrev_b32_e32 v160, 16, v199
	v_rcp_f32_e32 v161, v161
	v_rcp_f32_e32 v160, v160
	v_lshlrev_b32_e32 v162, 16, v195
	v_and_b32_e32 v163, 0xffff0000, v195
	v_pk_mul_f32 v[34:35], v[34:35], v[156:157]
	v_pk_mul_f32 v[160:161], v[160:161], v[162:163]
	s_nop 0
	v_pk_mul_f32 v[36:37], v[36:37], v[160:161]
	v_add_u32_e32 v154, 0x1e0000, v153
	global_load_dwordx4 v[168:171], v154, s[10:11]
	global_load_dwordx4 v[172:175], v154, s[100:101]
	global_load_dwordx4 v[176:179], v154, s[10:11] offset:256
	global_load_dwordx4 v[180:183], v154, s[100:101] offset:256
	v_add_u32_e32 v155, 0x210000, v153
	global_load_dwordx4 v[184:187], v155, s[10:11]
	global_load_dwordx4 v[188:191], v155, s[100:101]
	global_load_dwordx4 v[192:195], v155, s[10:11] offset:256
	global_load_dwordx4 v[196:199], v155, s[100:101] offset:256
	s_waitcnt vmcnt(0)
	v_and_b32_e32 v157, 0xffff0000, v172
	v_lshlrev_b32_e32 v156, 16, v172
	v_rcp_f32_e32 v157, v157
	v_rcp_f32_e32 v156, v156
	v_lshlrev_b32_e32 v158, 16, v168
	v_and_b32_e32 v159, 0xffff0000, v168
	v_pk_mul_f32 v[156:157], v[156:157], v[158:159]
	v_and_b32_e32 v161, 0xffff0000, v173
	v_lshlrev_b32_e32 v160, 16, v173
	v_rcp_f32_e32 v161, v161
	v_rcp_f32_e32 v160, v160
	v_lshlrev_b32_e32 v162, 16, v169
	v_and_b32_e32 v163, 0xffff0000, v169
	v_pk_mul_f32 v[30:31], v[30:31], v[156:157]
	v_pk_mul_f32 v[160:161], v[160:161], v[162:163]
	v_and_b32_e32 v157, 0xffff0000, v174
	v_lshlrev_b32_e32 v156, 16, v174
	v_rcp_f32_e32 v157, v157
	v_rcp_f32_e32 v156, v156
	v_lshlrev_b32_e32 v158, 16, v170
	v_and_b32_e32 v159, 0xffff0000, v170
	v_pk_mul_f32 v[32:33], v[32:33], v[160:161]
	v_pk_mul_f32 v[156:157], v[156:157], v[158:159]
	v_and_b32_e32 v161, 0xffff0000, v175
	v_lshlrev_b32_e32 v160, 16, v175
	v_rcp_f32_e32 v161, v161
	v_rcp_f32_e32 v160, v160
	v_lshlrev_b32_e32 v162, 16, v171
	v_and_b32_e32 v163, 0xffff0000, v171
	v_pk_mul_f32 v[26:27], v[26:27], v[156:157]
	v_pk_mul_f32 v[160:161], v[160:161], v[162:163]
	v_and_b32_e32 v157, 0xffff0000, v180
	v_lshlrev_b32_e32 v156, 16, v180
	v_rcp_f32_e32 v157, v157
	v_rcp_f32_e32 v156, v156
	v_lshlrev_b32_e32 v158, 16, v176
	v_and_b32_e32 v159, 0xffff0000, v176
	v_pk_mul_f32 v[28:29], v[28:29], v[160:161]
	v_pk_mul_f32 v[156:157], v[156:157], v[158:159]
	v_and_b32_e32 v161, 0xffff0000, v181
	v_lshlrev_b32_e32 v160, 16, v181
	v_rcp_f32_e32 v161, v161
	v_rcp_f32_e32 v160, v160
	v_lshlrev_b32_e32 v162, 16, v177
	v_and_b32_e32 v163, 0xffff0000, v177
	v_pk_mul_f32 v[22:23], v[22:23], v[156:157]
	v_pk_mul_f32 v[160:161], v[160:161], v[162:163]
	v_and_b32_e32 v157, 0xffff0000, v182
	v_lshlrev_b32_e32 v156, 16, v182
	v_rcp_f32_e32 v157, v157
	v_rcp_f32_e32 v156, v156
	v_lshlrev_b32_e32 v158, 16, v178
	v_and_b32_e32 v159, 0xffff0000, v178
	v_pk_mul_f32 v[24:25], v[24:25], v[160:161]
	v_pk_mul_f32 v[156:157], v[156:157], v[158:159]
	v_and_b32_e32 v161, 0xffff0000, v183
	v_lshlrev_b32_e32 v160, 16, v183
	v_rcp_f32_e32 v161, v161
	v_rcp_f32_e32 v160, v160
	v_lshlrev_b32_e32 v162, 16, v179
	v_and_b32_e32 v163, 0xffff0000, v179
	v_pk_mul_f32 v[18:19], v[18:19], v[156:157]
	v_pk_mul_f32 v[160:161], v[160:161], v[162:163]
	v_and_b32_e32 v157, 0xffff0000, v188
	v_lshlrev_b32_e32 v156, 16, v188
	v_rcp_f32_e32 v157, v157
	v_rcp_f32_e32 v156, v156
	v_lshlrev_b32_e32 v158, 16, v184
	v_and_b32_e32 v159, 0xffff0000, v184
	v_pk_mul_f32 v[20:21], v[20:21], v[160:161]
	v_pk_mul_f32 v[156:157], v[156:157], v[158:159]
	v_and_b32_e32 v161, 0xffff0000, v189
	v_lshlrev_b32_e32 v160, 16, v189
	v_rcp_f32_e32 v161, v161
	v_rcp_f32_e32 v160, v160
	v_lshlrev_b32_e32 v162, 16, v185
	v_and_b32_e32 v163, 0xffff0000, v185
	v_pk_mul_f32 v[14:15], v[14:15], v[156:157]
	v_pk_mul_f32 v[160:161], v[160:161], v[162:163]
	v_and_b32_e32 v157, 0xffff0000, v190
	v_lshlrev_b32_e32 v156, 16, v190
	v_rcp_f32_e32 v157, v157
	v_rcp_f32_e32 v156, v156
	v_lshlrev_b32_e32 v158, 16, v186
	v_and_b32_e32 v159, 0xffff0000, v186
	v_pk_mul_f32 v[16:17], v[16:17], v[160:161]
	v_pk_mul_f32 v[156:157], v[156:157], v[158:159]
	v_and_b32_e32 v161, 0xffff0000, v191
	v_lshlrev_b32_e32 v160, 16, v191
	v_rcp_f32_e32 v161, v161
	v_rcp_f32_e32 v160, v160
	v_lshlrev_b32_e32 v162, 16, v187
	v_and_b32_e32 v163, 0xffff0000, v187
	v_pk_mul_f32 v[10:11], v[10:11], v[156:157]
	v_pk_mul_f32 v[160:161], v[160:161], v[162:163]
	v_and_b32_e32 v157, 0xffff0000, v196
	v_lshlrev_b32_e32 v156, 16, v196
	v_rcp_f32_e32 v157, v157
	v_rcp_f32_e32 v156, v156
	v_lshlrev_b32_e32 v158, 16, v192
	v_and_b32_e32 v159, 0xffff0000, v192
	v_pk_mul_f32 v[12:13], v[12:13], v[160:161]
	v_pk_mul_f32 v[156:157], v[156:157], v[158:159]
	v_and_b32_e32 v161, 0xffff0000, v197
	v_lshlrev_b32_e32 v160, 16, v197
	v_rcp_f32_e32 v161, v161
	v_rcp_f32_e32 v160, v160
	v_lshlrev_b32_e32 v162, 16, v193
	v_and_b32_e32 v163, 0xffff0000, v193
	v_pk_mul_f32 v[6:7], v[6:7], v[156:157]
	v_pk_mul_f32 v[160:161], v[160:161], v[162:163]
	v_and_b32_e32 v157, 0xffff0000, v198
	v_lshlrev_b32_e32 v156, 16, v198
	v_rcp_f32_e32 v157, v157
	v_rcp_f32_e32 v156, v156
	v_lshlrev_b32_e32 v158, 16, v194
	v_and_b32_e32 v159, 0xffff0000, v194
	v_pk_mul_f32 v[8:9], v[8:9], v[160:161]
	v_pk_mul_f32 v[156:157], v[156:157], v[158:159]
	v_and_b32_e32 v161, 0xffff0000, v199
	v_lshlrev_b32_e32 v160, 16, v199
	v_rcp_f32_e32 v161, v161
	v_rcp_f32_e32 v160, v160
	v_lshlrev_b32_e32 v162, 16, v195
	v_and_b32_e32 v163, 0xffff0000, v195
	v_pk_mul_f32 v[2:3], v[2:3], v[156:157]
	v_pk_mul_f32 v[160:161], v[160:161], v[162:163]
	s_nop 0
	v_pk_mul_f32 v[4:5], v[4:5], v[160:161]
	s_branch .LBB0_1290

.LBB0_2000:
	s_lshl_b32 s12, s20, 6
	s_cmp_lt_i32 s66, 0
	s_mov_b64 s[16:17], -1
	s_cbranch_scc1 .LBB0_2066
	s_lshl_b64 s[16:17], s[66:67], 2
	s_add_u32 s4, s4, s16
	v_add_u32_e32 v8, s12, v3
	s_addc_u32 s5, s5, s17
	v_ashrrev_i32_e32 v9, 31, v8
	v_lshl_add_u64 v[4:5], s[4:5], 0, v[0:1]
	v_mul_lo_u32 v20, s8, v9
	v_mul_lo_u32 v21, s9, v8
	v_mad_u64_u32 v[6:7], s[4:5], s8, v8, 0
	v_add3_u32 v7, v7, v20, v21
	v_lshl_add_u64 v[6:7], v[6:7], 2, v[4:5]
	s_lshl_b64 s[16:17], s[8:9], 3
	global_load_dword v100, v[6:7], off nt
	v_lshl_add_u64 v[6:7], v[6:7], 0, s[16:17]
	global_load_dword v101, v[6:7], off nt
	v_lshl_add_u64 v[6:7], v[6:7], 0, s[16:17]
	global_load_dword v102, v[6:7], off nt
	v_lshl_add_u64 v[6:7], v[6:7], 0, s[16:17]
	global_load_dword v103, v[6:7], off nt
	v_lshl_add_u64 v[6:7], v[6:7], 0, s[16:17]
	global_load_dword v104, v[6:7], off nt
	v_lshl_add_u64 v[6:7], v[6:7], 0, s[16:17]
	global_load_dword v105, v[6:7], off nt
	v_lshl_add_u64 v[6:7], v[6:7], 0, s[16:17]
	global_load_dword v106, v[6:7], off nt
	v_lshl_add_u64 v[6:7], v[6:7], 0, s[16:17]
	global_load_dword v107, v[6:7], off nt
	v_lshl_add_u64 v[6:7], v[6:7], 0, s[16:17]
	global_load_dword v108, v[6:7], off nt
	v_lshl_add_u64 v[6:7], v[6:7], 0, s[16:17]
	global_load_dword v109, v[6:7], off nt
	v_lshl_add_u64 v[6:7], v[6:7], 0, s[16:17]
	global_load_dword v110, v[6:7], off nt
	v_lshl_add_u64 v[6:7], v[6:7], 0, s[16:17]
	global_load_dword v111, v[6:7], off nt
	v_lshl_add_u64 v[6:7], v[6:7], 0, s[16:17]
	global_load_dword v112, v[6:7], off nt
	v_lshl_add_u64 v[6:7], v[6:7], 0, s[16:17]
	global_load_dword v113, v[6:7], off nt
	v_lshl_add_u64 v[6:7], v[6:7], 0, s[16:17]
	global_load_dword v114, v[6:7], off nt
	v_lshl_add_u64 v[6:7], v[6:7], 0, s[16:17]
	global_load_dword v115, v[6:7], off nt
	v_lshl_add_u64 v[6:7], v[6:7], 0, s[16:17]
	global_load_dword v116, v[6:7], off nt
	v_lshl_add_u64 v[6:7], v[6:7], 0, s[16:17]
	global_load_dword v117, v[6:7], off nt
	v_lshl_add_u64 v[6:7], v[6:7], 0, s[16:17]
	global_load_dword v118, v[6:7], off nt
	v_lshl_add_u64 v[6:7], v[6:7], 0, s[16:17]
	global_load_dword v119, v[6:7], off nt
	v_lshl_add_u64 v[6:7], v[6:7], 0, s[16:17]
	global_load_dword v120, v[6:7], off nt
	v_lshl_add_u64 v[6:7], v[6:7], 0, s[16:17]
	global_load_dword v121, v[6:7], off nt
	v_lshl_add_u64 v[6:7], v[6:7], 0, s[16:17]
	global_load_dword v122, v[6:7], off nt
	v_lshl_add_u64 v[6:7], v[6:7], 0, s[16:17]
	global_load_dword v123, v[6:7], off nt
	v_lshl_add_u64 v[6:7], v[6:7], 0, s[16:17]
	global_load_dword v124, v[6:7], off nt
	v_lshl_add_u64 v[6:7], v[6:7], 0, s[16:17]
	global_load_dword v125, v[6:7], off nt
	v_lshl_add_u64 v[6:7], v[6:7], 0, s[16:17]
	global_load_dword v126, v[6:7], off nt
	v_lshl_add_u64 v[6:7], v[6:7], 0, s[16:17]
	global_load_dword v127, v[6:7], off nt
	v_lshl_add_u64 v[6:7], v[6:7], 0, s[16:17]
	global_load_dword v128, v[6:7], off nt
	v_lshl_add_u64 v[6:7], v[6:7], 0, s[16:17]
	global_load_dword v129, v[6:7], off nt
	v_lshl_add_u64 v[6:7], v[6:7], 0, s[16:17]
	global_load_dword v130, v[6:7], off nt
	v_lshl_add_u64 v[6:7], v[6:7], 0, s[16:17]
	global_load_dword v131, v[6:7], off nt
	s_cmp_lg_u64 s[14:15], 0
	s_cbranch_scc0 .Ltr1_noscale
	v_lshl_add_u64 v[20:21], v[8:9], 2, s[14:15]
	global_load_dword v132, v[20:21], off
	global_load_dword v133, v[20:21], off offset:8
	global_load_dword v134, v[20:21], off offset:16
	global_load_dword v135, v[20:21], off offset:24
	global_load_dword v136, v[20:21], off offset:32
	global_load_dword v137, v[20:21], off offset:40
	global_load_dword v138, v[20:21], off offset:48
	global_load_dword v139, v[20:21], off offset:56
	global_load_dword v140, v[20:21], off offset:64
	global_load_dword v141, v[20:21], off offset:72
	global_load_dword v142, v[20:21], off offset:80
	global_load_dword v143, v[20:21], off offset:88
	global_load_dword v144, v[20:21], off offset:96
	global_load_dword v145, v[20:21], off offset:104
	global_load_dword v146, v[20:21], off offset:112
	global_load_dword v147, v[20:21], off offset:120
	global_load_dword v148, v[20:21], off offset:128
	global_load_dword v149, v[20:21], off offset:136
	global_load_dword v150, v[20:21], off offset:144
	global_load_dword v151, v[20:21], off offset:152
	global_load_dword v152, v[20:21], off offset:160
	global_load_dword v153, v[20:21], off offset:168
	global_load_dword v154, v[20:21], off offset:176
	global_load_dword v155, v[20:21], off offset:184
	global_load_dword v156, v[20:21], off offset:192
	global_load_dword v157, v[20:21], off offset:200
	global_load_dword v158, v[20:21], off offset:208
	global_load_dword v159, v[20:21], off offset:216
	global_load_dword v160, v[20:21], off offset:224
	global_load_dword v161, v[20:21], off offset:232
	global_load_dword v162, v[20:21], off offset:240
	global_load_dword v163, v[20:21], off offset:248
	s_waitcnt vmcnt(0)
	v_mul_f32_e32 v100, v100, v132
	v_mul_f32_e32 v101, v101, v133
	v_mul_f32_e32 v102, v102, v134
	v_mul_f32_e32 v103, v103, v135
	v_mul_f32_e32 v104, v104, v136
	v_mul_f32_e32 v105, v105, v137
	v_mul_f32_e32 v106, v106, v138
	v_mul_f32_e32 v107, v107, v139
	v_mul_f32_e32 v108, v108, v140
	v_mul_f32_e32 v109, v109, v141
	v_mul_f32_e32 v110, v110, v142
	v_mul_f32_e32 v111, v111, v143
	v_mul_f32_e32 v112, v112, v144
	v_mul_f32_e32 v113, v113, v145
	v_mul_f32_e32 v114, v114, v146
	v_mul_f32_e32 v115, v115, v147
	v_mul_f32_e32 v116, v116, v148
	v_mul_f32_e32 v117, v117, v149
	v_mul_f32_e32 v118, v118, v150
	v_mul_f32_e32 v119, v119, v151
	v_mul_f32_e32 v120, v120, v152
	v_mul_f32_e32 v121, v121, v153
	v_mul_f32_e32 v122, v122, v154
	v_mul_f32_e32 v123, v123, v155
	v_mul_f32_e32 v124, v124, v156
	v_mul_f32_e32 v125, v125, v157
	v_mul_f32_e32 v126, v126, v158
	v_mul_f32_e32 v127, v127, v159
	v_mul_f32_e32 v128, v128, v160
	v_mul_f32_e32 v129, v129, v161
	v_mul_f32_e32 v130, v130, v162
	v_mul_f32_e32 v131, v131, v163
.Ltr1_noscale:
	s_waitcnt vmcnt(0)
	ds_write_b32 v19, v100
	ds_write_b32 v19, v101 offset:264
	ds_write_b32 v19, v102 offset:528
	ds_write_b32 v19, v103 offset:792
	ds_write_b32 v19, v104 offset:1056
	ds_write_b32 v19, v105 offset:1320
	ds_write_b32 v19, v106 offset:1584
	ds_write_b32 v19, v107 offset:1848
	ds_write_b32 v19, v108 offset:2112
	ds_write_b32 v19, v109 offset:2376
	ds_write_b32 v19, v110 offset:2640
	ds_write_b32 v19, v111 offset:2904
	ds_write_b32 v19, v112 offset:3168
	ds_write_b32 v19, v113 offset:3432
	ds_write_b32 v19, v114 offset:3696
	ds_write_b32 v19, v115 offset:3960
	ds_write_b32 v19, v116 offset:4224
	ds_write_b32 v19, v117 offset:4488
	ds_write_b32 v19, v118 offset:4752
	ds_write_b32 v19, v119 offset:5016
	ds_write_b32 v19, v120 offset:5280
	ds_write_b32 v19, v121 offset:5544
	ds_write_b32 v19, v122 offset:5808
	ds_write_b32 v19, v123 offset:6072
	ds_write_b32 v19, v124 offset:6336
	ds_write_b32 v19, v125 offset:6600
	ds_write_b32 v19, v126 offset:6864
	ds_write_b32 v19, v127 offset:7128
	ds_write_b32 v19, v128 offset:7392
	ds_write_b32 v19, v129 offset:7656
	ds_write_b32 v19, v130 offset:7920
	ds_write_b32 v19, v131 offset:8184
	s_ashr_i32 s13, s12, 31
	s_lshl_b64 s[4:5], s[12:13], 1
	s_add_u32 s4, s2, s4
	s_addc_u32 s5, s3, s5
	v_lshlrev_b32_e32 v4, 1, v2
	v_mov_b32_e32 v5, v1
	v_lshl_add_u64 v[8:9], s[4:5], 0, v[4:5]
	v_cndmask_b32_e64 v4, v10, v12, s[10:11]
	s_waitcnt lgkmcnt(0)
	v_lshl_add_u32 v20, v4, 2, v11
	ds_read2_b32 v[4:5], v20 offset1:33
	ds_read2_b32 v[6:7], v20 offset0:66 offset1:99
	s_waitcnt lgkmcnt(1)
	v_cvt_pk_bf16_f32 v4, v4, v5
	s_waitcnt lgkmcnt(0)
	v_cvt_pk_bf16_f32 v5, v6, v7
	ds_read2_b32 v[6:7], v20 offset0:132 offset1:165
	ds_read2_b32 v[20:21], v20 offset0:198 offset1:231
	s_waitcnt lgkmcnt(1)
	v_cvt_pk_bf16_f32 v6, v6, v7
	s_waitcnt lgkmcnt(0)
	v_cvt_pk_bf16_f32 v7, v20, v21
	v_add_u32_e32 v20, s19, v10
	v_ashrrev_i32_e32 v21, 31, v20
	v_mul_lo_u32 v22, s6, v21
	v_mul_lo_u32 v23, s7, v20
	v_mad_u64_u32 v[20:21], s[4:5], s6, v20, 0
	v_add3_u32 v21, v21, v22, v23
	v_lshl_add_u64 v[20:21], v[20:21], 1, v[8:9]
	global_store_dwordx4 v[20:21], v[4:7], off
	s_nop 1
	v_cndmask_b32_e64 v4, v13, v14, s[10:11]
	v_lshl_add_u32 v20, v4, 2, v11
	ds_read2_b32 v[4:5], v20 offset1:33
	ds_read2_b32 v[6:7], v20 offset0:66 offset1:99
	s_waitcnt lgkmcnt(1)
	v_cvt_pk_bf16_f32 v4, v4, v5
	s_waitcnt lgkmcnt(0)
	v_cvt_pk_bf16_f32 v5, v6, v7
	ds_read2_b32 v[6:7], v20 offset0:132 offset1:165
	ds_read2_b32 v[20:21], v20 offset0:198 offset1:231
	s_waitcnt lgkmcnt(1)
	v_cvt_pk_bf16_f32 v6, v6, v7
	s_waitcnt lgkmcnt(0)
	v_cvt_pk_bf16_f32 v7, v20, v21
	v_add_u32_e32 v20, s19, v13
	v_ashrrev_i32_e32 v21, 31, v20
	v_mul_lo_u32 v22, s6, v21
	v_mul_lo_u32 v23, s7, v20
	v_mad_u64_u32 v[20:21], s[4:5], s6, v20, 0
	v_add3_u32 v21, v21, v22, v23
	v_lshl_add_u64 v[20:21], v[20:21], 1, v[8:9]
	global_store_dwordx4 v[20:21], v[4:7], off
	s_nop 1
	v_cndmask_b32_e64 v4, v15, v16, s[10:11]
	v_lshl_add_u32 v20, v4, 2, v11
	ds_read2_b32 v[4:5], v20 offset1:33
	ds_read2_b32 v[6:7], v20 offset0:66 offset1:99
	s_waitcnt lgkmcnt(1)
	v_cvt_pk_bf16_f32 v4, v4, v5
	s_waitcnt lgkmcnt(0)
	v_cvt_pk_bf16_f32 v5, v6, v7
	ds_read2_b32 v[6:7], v20 offset0:132 offset1:165
	ds_read2_b32 v[20:21], v20 offset0:198 offset1:231
	s_waitcnt lgkmcnt(1)
	v_cvt_pk_bf16_f32 v6, v6, v7
	s_waitcnt lgkmcnt(0)
	v_cvt_pk_bf16_f32 v7, v20, v21
	v_add_u32_e32 v20, s19, v15
	v_ashrrev_i32_e32 v21, 31, v20
	v_mul_lo_u32 v22, s6, v21
	v_mul_lo_u32 v23, s7, v20
	v_mad_u64_u32 v[20:21], s[4:5], s6, v20, 0
	v_add3_u32 v21, v21, v22, v23
	v_lshl_add_u64 v[20:21], v[20:21], 1, v[8:9]
	global_store_dwordx4 v[20:21], v[4:7], off
	s_nop 1
	v_cndmask_b32_e64 v4, v17, v18, s[10:11]
	v_lshl_add_u32 v20, v4, 2, v11
	ds_read2_b32 v[4:5], v20 offset1:33
	ds_read2_b32 v[6:7], v20 offset0:66 offset1:99
	s_waitcnt lgkmcnt(1)
	v_cvt_pk_bf16_f32 v4, v4, v5
	s_waitcnt lgkmcnt(0)
	v_cvt_pk_bf16_f32 v5, v6, v7
	ds_read2_b32 v[6:7], v20 offset0:132 offset1:165
	ds_read2_b32 v[20:21], v20 offset0:198 offset1:231
	s_waitcnt lgkmcnt(1)
	v_cvt_pk_bf16_f32 v6, v6, v7
	s_waitcnt lgkmcnt(0)
	v_cvt_pk_bf16_f32 v7, v20, v21
	v_add_u32_e32 v20, s19, v17
	v_ashrrev_i32_e32 v21, 31, v20
	v_mul_lo_u32 v22, s6, v21
	v_mul_lo_u32 v23, s7, v20
	v_mad_u64_u32 v[20:21], s[4:5], s6, v20, 0
	v_add3_u32 v21, v21, v22, v23
	v_lshl_add_u64 v[8:9], v[20:21], 1, v[8:9]
	global_store_dwordx4 v[8:9], v[4:7], off
	s_waitcnt lgkmcnt(0)
	s_branch .LBB0_1925

	.amdhsa_kernel _Z10fwd_kernel4Args
		.amdhsa_group_segment_fixed_size 0
		.amdhsa_private_segment_fixed_size 0
		.amdhsa_kernarg_size 560
		.amdhsa_user_sgpr_count 2
		.amdhsa_user_sgpr_dispatch_ptr 0
		.amdhsa_user_sgpr_queue_ptr 0
		.amdhsa_user_sgpr_kernarg_segment_ptr 1
		.amdhsa_user_sgpr_dispatch_id 0
		.amdhsa_user_sgpr_kernarg_preload_length 0
		.amdhsa_user_sgpr_kernarg_preload_offset 0
		.amdhsa_user_sgpr_private_segment_size 0
		.amdhsa_uses_dynamic_stack 0
		.amdhsa_enable_private_segment 0
		.amdhsa_system_sgpr_workgroup_id_x 1
		.amdhsa_system_sgpr_workgroup_id_y 0
		.amdhsa_system_sgpr_workgroup_id_z 0
		.amdhsa_system_sgpr_workgroup_info 0
		.amdhsa_system_vgpr_workitem_id 2
		.amdhsa_next_free_vgpr 256
		.amdhsa_next_free_sgpr 102
		.amdhsa_accum_offset 256
		.amdhsa_reserve_vcc 1
		.amdhsa_float_round_mode_32 0
		.amdhsa_float_round_mode_16_64 0
		.amdhsa_float_denorm_mode_32 3
		.amdhsa_float_denorm_mode_16_64 3
		.amdhsa_dx10_clamp 1
		.amdhsa_ieee_mode 1
		.amdhsa_fp16_overflow 0
		.amdhsa_tg_split 0
		.amdhsa_exception_fp_ieee_invalid_op 0
		.amdhsa_exception_fp_denorm_src 0
		.amdhsa_exception_fp_ieee_div_zero 0
		.amdhsa_exception_fp_ieee_overflow 0
		.amdhsa_exception_fp_ieee_underflow 0
		.amdhsa_exception_fp_ieee_inexact 0
		.amdhsa_exception_int_div_zero 0
	.end_amdhsa_kernel

amdhsa.kernels:
  - .agpr_count:     0
    .args:
      - .offset:         0
        .size:           304
        .value_kind:     by_value
      - .offset:         304
        .size:           4
        .value_kind:     hidden_block_count_x
      - .offset:         308
        .size:           4
        .value_kind:     hidden_block_count_y
      - .offset:         312
        .size:           4
        .value_kind:     hidden_block_count_z
      - .offset:         316
        .size:           2
        .value_kind:     hidden_group_size_x
      - .offset:         318
        .size:           2
        .value_kind:     hidden_group_size_y
      - .offset:         320
        .size:           2
        .value_kind:     hidden_group_size_z
      - .offset:         322
        .size:           2
        .value_kind:     hidden_remainder_x
      - .offset:         324
        .size:           2
        .value_kind:     hidden_remainder_y
      - .offset:         326
        .size:           2
        .value_kind:     hidden_remainder_z
      - .offset:         344
        .size:           8
        .value_kind:     hidden_global_offset_x
      - .offset:         352
        .size:           8
        .value_kind:     hidden_global_offset_y
      - .offset:         360
        .size:           8
        .value_kind:     hidden_global_offset_z
      - .offset:         368
        .size:           2
        .value_kind:     hidden_grid_dims
      - .offset:         392
        .size:           8
        .value_kind:     hidden_multigrid_sync_arg
      - .offset:         424
        .size:           4
        .value_kind:     hidden_dynamic_lds_size
    .group_segment_fixed_size: 0
    .kernarg_segment_align: 8
    .kernarg_segment_size: 560
    .language:       OpenCL C
    .language_version:
      - 2
      - 0
    .max_flat_workgroup_size: 512
    .name:           _Z10fwd_kernel4Args
    .private_segment_fixed_size: 0
    .sgpr_count:     108
    .sgpr_spill_count: 74
    .symbol:         _Z10fwd_kernel4Args.kd
    .uniform_work_group_size: 1
    .uses_dynamic_stack: false
    .vgpr_count:     256
    .vgpr_spill_count: 0
    .wavefront_size: 64
